# v27 + NA attention QK stage: all four K-fragment ds_reads issued up front with counted waits instead of read-wait-MFMA serialisation (strategy: waitcnt placement / counted waits)
# speedup vs baseline: 1.0006x; 1.0006x over previous
; template <int DQ, bool NA, int NQG>
; DI void attn_wg(const half_t* Qp, const half_t* Kp, const half_t* Vp, int q0, bool active, int seg0_start, int seg0_tiles,
;                 int seg1_start, int seg1_tiles, const float* rpb_h, int rq, char* smem, int tid, f16v (&O)[2][NQG]) {
;     ...
;         for (int ks = 0; ks < NKS; ++ks) {
;           const h8 kf = *(const h8*)(ksm + (st * 32) * KSTR + ks * 16);
; #pragma unroll
;           for (int qg = 0; qg < NQG; ++qg) S[qg] = __builtin_amdgcn_mfma_f32_32x32x16_f16(kf, qf[qg][ks], S[qg], 0, 0, 0);
;         }
;         if (masked) {
;           const int cb = st * 32;
;           const int dr = krow - rq + 7;
; #pragma unroll
;           for (int qg = 0; qg < NQG; ++qg) {
;             const int qc = qg * 32 + r;
;             const int cs = min(max(qc - 8, 0), 48);
; #pragma unroll
;             for (int i = 0; i < 16; ++i) {
;               const int c = cb + (i & 3) + 8 * (i >> 2) + 4 * h;
;               const bool valid = (c >= cs) && (c < cs + 16);
;               float bias = 0.f;
;               if (valid) bias = rpb_h[dr * 31 + (c - qc + 15)] * LOG2E;
;               S[qg][i] = valid ? S[qg][i] + bias : -1e30f;
;             }
;           }
.LBB0_2095:
	s_mul_i32 s8, s46, 0x1200
	v_add_u32_e32 v6, s8, v1
	ds_read_b128 v[2:5], v6
	ds_read_b128 v[204:207], v6 offset:32
	ds_read_b128 v[208:211], v6 offset:64
	ds_read_b128 v[212:215], v6 offset:96
	s_andn2_b64 vcc, exec, s[26:27]
	s_waitcnt lgkmcnt(3)
	v_mfma_f32_32x32x16_f16 v[96:111], v[2:5], v[112:115], 0
	v_mfma_f32_32x32x16_f16 v[80:95], v[2:5], v[128:131], 0
	s_waitcnt lgkmcnt(2)
	v_mfma_f32_32x32x16_f16 v[96:111], v[204:207], v[116:119], v[96:111]
	v_mfma_f32_32x32x16_f16 v[80:95], v[204:207], v[132:135], v[80:95]
	s_waitcnt lgkmcnt(1)
	v_mfma_f32_32x32x16_f16 v[96:111], v[208:211], v[120:123], v[96:111]
	v_mfma_f32_32x32x16_f16 v[80:95], v[208:211], v[136:139], v[80:95]
	s_waitcnt lgkmcnt(0)
	v_mfma_f32_32x32x16_f16 v[96:111], v[212:215], v[124:127], v[96:111]
	v_mfma_f32_32x32x16_f16 v[80:95], v[212:215], v[140:143], v[80:95]
	s_cbranch_vccnz .LBB0_2161
	s_lshl_b32 s40, s46, 7
	v_add_u32_e32 v2, v160, v181
	v_add_u32_e32 v3, v162, v181
	v_lshl_add_u32 v2, v2, 2, s40
	v_lshl_add_u32 v3, v3, 2, s40
	v_add_u32_e32 v2, 0x1c000, v2
	v_add_u32_e32 v3, 0x1c000, v3
	ds_read2_b32 v[168:169], v2 offset0:0 offset1:1
	ds_read2_b32 v[170:171], v2 offset0:2 offset1:3
	ds_read2_b32 v[206:207], v2 offset0:8 offset1:9
	ds_read2_b32 v[210:211], v2 offset0:10 offset1:11
	ds_read2_b32 v[212:213], v2 offset0:16 offset1:17
	ds_read2_b32 v[218:219], v2 offset0:18 offset1:19
	ds_read2_b32 v[222:223], v2 offset0:24 offset1:25
	ds_read2_b32 v[226:227], v2 offset0:26 offset1:27
	ds_read2_b32 v[172:173], v3 offset0:0 offset1:1
	ds_read2_b32 v[204:205], v3 offset0:2 offset1:3
	ds_read2_b32 v[208:209], v3 offset0:8 offset1:9
	ds_read2_b32 v[214:215], v3 offset0:10 offset1:11
	ds_read2_b32 v[216:217], v3 offset0:16 offset1:17
	ds_read2_b32 v[220:221], v3 offset0:18 offset1:19
	ds_read2_b32 v[224:225], v3 offset0:24 offset1:25
	ds_read2_b32 v[228:229], v3 offset0:26 offset1:27
	v_lshl_or_b32 v11, s46, 5, v181
	v_sub_u32_e32 v4, v11, v233
	v_sub_u32_e32 v5, v11, v236
	v_mov_b32_e32 v10, 0xf149f2ca
	s_waitcnt lgkmcnt(0)
	v_add_u32_e32 v6, 0, v4
	v_add_u32_e32 v7, 1, v4
	v_add_u32_e32 v8, 2, v4
	v_add_u32_e32 v9, 3, v4
	v_cmp_gt_u32_e32 vcc, 16, v6
	v_cmp_gt_u32_e64 s[8:9], 16, v7
	v_cmp_gt_u32_e64 s[74:75], 16, v8
	v_cmp_gt_u32_e64 s[78:79], 16, v9
	v_fmamk_f32 v168, v168, 0x3fb8aa3b, v96
	v_fmamk_f32 v169, v169, 0x3fb8aa3b, v97
	v_fmamk_f32 v170, v170, 0x3fb8aa3b, v98
	v_fmamk_f32 v171, v171, 0x3fb8aa3b, v99
	v_cndmask_b32_e32 v168, v10, v168, vcc
	v_cndmask_b32_e64 v169, v10, v169, s[8:9]
	v_cndmask_b32_e64 v170, v10, v170, s[74:75]
	v_cndmask_b32_e64 v171, v10, v171, s[78:79]
	v_add_u32_e32 v6, 8, v4
	v_add_u32_e32 v7, 9, v4
	v_add_u32_e32 v8, 10, v4
	v_add_u32_e32 v9, 11, v4
	v_cmp_gt_u32_e32 vcc, 16, v6
	v_cmp_gt_u32_e64 s[8:9], 16, v7
	v_cmp_gt_u32_e64 s[74:75], 16, v8
	v_cmp_gt_u32_e64 s[78:79], 16, v9
	v_fmamk_f32 v206, v206, 0x3fb8aa3b, v100
	v_fmamk_f32 v207, v207, 0x3fb8aa3b, v101
	v_fmamk_f32 v210, v210, 0x3fb8aa3b, v102
	v_fmamk_f32 v211, v211, 0x3fb8aa3b, v103
	v_cndmask_b32_e32 v206, v10, v206, vcc
	v_cndmask_b32_e64 v207, v10, v207, s[8:9]
	v_cndmask_b32_e64 v210, v10, v210, s[74:75]
	v_cndmask_b32_e64 v211, v10, v211, s[78:79]
	v_add_u32_e32 v6, 16, v4
	v_add_u32_e32 v7, 17, v4
	v_add_u32_e32 v8, 18, v4
	v_add_u32_e32 v9, 19, v4
	v_cmp_gt_u32_e32 vcc, 16, v6
	v_cmp_gt_u32_e64 s[8:9], 16, v7
	v_cmp_gt_u32_e64 s[74:75], 16, v8
	v_cmp_gt_u32_e64 s[78:79], 16, v9
	v_fmamk_f32 v212, v212, 0x3fb8aa3b, v104
	v_fmamk_f32 v213, v213, 0x3fb8aa3b, v105
	v_fmamk_f32 v218, v218, 0x3fb8aa3b, v106
	v_fmamk_f32 v219, v219, 0x3fb8aa3b, v107
	v_cndmask_b32_e32 v212, v10, v212, vcc
	v_cndmask_b32_e64 v213, v10, v213, s[8:9]
	v_cndmask_b32_e64 v218, v10, v218, s[74:75]
	v_cndmask_b32_e64 v219, v10, v219, s[78:79]
	v_add_u32_e32 v6, 24, v4
	v_add_u32_e32 v7, 25, v4
	v_add_u32_e32 v8, 26, v4
	v_add_u32_e32 v9, 27, v4
	v_cmp_gt_u32_e32 vcc, 16, v6
	v_cmp_gt_u32_e64 s[8:9], 16, v7
	v_cmp_gt_u32_e64 s[74:75], 16, v8
	v_cmp_gt_u32_e64 s[78:79], 16, v9
	v_fmamk_f32 v222, v222, 0x3fb8aa3b, v108
	v_fmamk_f32 v223, v223, 0x3fb8aa3b, v109
	v_fmamk_f32 v226, v226, 0x3fb8aa3b, v110
	v_fmamk_f32 v227, v227, 0x3fb8aa3b, v111
	v_cndmask_b32_e32 v222, v10, v222, vcc
	v_cndmask_b32_e64 v223, v10, v223, s[8:9]
	v_cndmask_b32_e64 v226, v10, v226, s[74:75]
	v_cndmask_b32_e64 v227, v10, v227, s[78:79]
	v_add_u32_e32 v6, 0, v5
	v_add_u32_e32 v7, 1, v5
	v_add_u32_e32 v8, 2, v5
	v_add_u32_e32 v9, 3, v5
	v_cmp_gt_u32_e32 vcc, 16, v6
	v_cmp_gt_u32_e64 s[8:9], 16, v7
	v_cmp_gt_u32_e64 s[74:75], 16, v8
	v_cmp_gt_u32_e64 s[78:79], 16, v9
	v_fmamk_f32 v172, v172, 0x3fb8aa3b, v80
	v_fmamk_f32 v173, v173, 0x3fb8aa3b, v81
	v_fmamk_f32 v204, v204, 0x3fb8aa3b, v82
	v_fmamk_f32 v205, v205, 0x3fb8aa3b, v83
	v_cndmask_b32_e32 v172, v10, v172, vcc
	v_cndmask_b32_e64 v173, v10, v173, s[8:9]
	v_cndmask_b32_e64 v204, v10, v204, s[74:75]
	v_cndmask_b32_e64 v205, v10, v205, s[78:79]
	v_add_u32_e32 v6, 8, v5
	v_add_u32_e32 v7, 9, v5
	v_add_u32_e32 v8, 10, v5
	v_add_u32_e32 v9, 11, v5
	v_cmp_gt_u32_e32 vcc, 16, v6
	v_cmp_gt_u32_e64 s[8:9], 16, v7
	v_cmp_gt_u32_e64 s[74:75], 16, v8
	v_cmp_gt_u32_e64 s[78:79], 16, v9
	v_fmamk_f32 v208, v208, 0x3fb8aa3b, v84
	v_fmamk_f32 v209, v209, 0x3fb8aa3b, v85
	v_fmamk_f32 v214, v214, 0x3fb8aa3b, v86
	v_fmamk_f32 v215, v215, 0x3fb8aa3b, v87
	v_cndmask_b32_e32 v208, v10, v208, vcc
	v_cndmask_b32_e64 v209, v10, v209, s[8:9]
	v_cndmask_b32_e64 v214, v10, v214, s[74:75]
	v_cndmask_b32_e64 v215, v10, v215, s[78:79]
	v_add_u32_e32 v6, 16, v5
	v_add_u32_e32 v7, 17, v5
	v_add_u32_e32 v8, 18, v5
	v_add_u32_e32 v9, 19, v5
	v_cmp_gt_u32_e32 vcc, 16, v6
	v_cmp_gt_u32_e64 s[8:9], 16, v7
	v_cmp_gt_u32_e64 s[74:75], 16, v8
	v_cmp_gt_u32_e64 s[78:79], 16, v9
	v_fmamk_f32 v216, v216, 0x3fb8aa3b, v88
	v_fmamk_f32 v217, v217, 0x3fb8aa3b, v89
	v_fmamk_f32 v220, v220, 0x3fb8aa3b, v90
	v_fmamk_f32 v221, v221, 0x3fb8aa3b, v91
	v_cndmask_b32_e32 v216, v10, v216, vcc
	v_cndmask_b32_e64 v217, v10, v217, s[8:9]
	v_cndmask_b32_e64 v220, v10, v220, s[74:75]
	v_cndmask_b32_e64 v221, v10, v221, s[78:79]
	v_add_u32_e32 v6, 24, v5
	v_add_u32_e32 v7, 25, v5
	v_add_u32_e32 v8, 26, v5
	v_add_u32_e32 v9, 27, v5
	v_cmp_gt_u32_e32 vcc, 16, v6
	v_cmp_gt_u32_e64 s[8:9], 16, v7
	v_cmp_gt_u32_e64 s[74:75], 16, v8
	v_cmp_gt_u32_e64 s[78:79], 16, v9
	v_fmamk_f32 v224, v224, 0x3fb8aa3b, v92
	v_fmamk_f32 v225, v225, 0x3fb8aa3b, v93
	v_fmamk_f32 v228, v228, 0x3fb8aa3b, v94
	v_fmamk_f32 v229, v229, 0x3fb8aa3b, v95
	v_cndmask_b32_e32 v224, v10, v224, vcc
	v_cndmask_b32_e64 v225, v10, v225, s[8:9]
	v_cndmask_b32_e64 v228, v10, v228, s[74:75]
	v_cndmask_b32_e64 v229, v10, v229, s[78:79]
	s_branch .LBB0_2162
